# v40 + grid barrier: non-leader work-groups spin on the top-level generation word directly (one hop) instead of the per-XCD generation word bumped by their XCD leader
# speedup vs baseline: 1.0054x; 1.0049x over previous
; __device__ __forceinline__ unsigned xb_ld(unsigned* p)              { return __hip_atomic_load(p, __ATOMIC_RELAXED, __HIP_MEMORY_SCOPE_AGENT); }
; __device__ __forceinline__ unsigned xb_add(unsigned* p, unsigned v) { return __hip_atomic_fetch_add(p, v, __ATOMIC_RELAXED, __HIP_MEMORY_SCOPE_AGENT); }
; #define XB_SPIN(cond, bar) do { unsigned _sp = 0; while (cond) { __builtin_amdgcn_s_sleep(1); \
;     if ((++_sp & 255u) == 0u) { if (xb_ld(&(bar)[XB_TMO])) break; if (_sp > XB_SPIN_CAP) { atomicAdd(&(bar)[XB_TMO], 1u); break; } } } } while (0)
; __device__ __forceinline__ void xcd_barrier(const XcdBarrier& b) {
;     ...
;         const unsigned old = xb_add(&bar[XB_XSUB(b.x)], 1u);
;         const unsigned gen = old / nloc;
;         if (old + 1u == (gen + 1u) * nloc) {
;             __builtin_amdgcn_fence(__ATOMIC_RELEASE, "agent");
;             asm volatile("s_waitcnt vmcnt(0)" ::: "memory");
;             const unsigned og = xb_add(&bar[XB_TOP], 1u);
;             const unsigned tg = og / nx;
;             if (og + 1u == (tg + 1u) * nx) xb_add(&bar[XB_TOPGEN], 1u);
;             else XB_SPIN(xb_ld(&bar[XB_TOPGEN]) == tg, bar);
;             __builtin_amdgcn_fence(__ATOMIC_ACQUIRE, "agent");
;             xb_add(&bar[XB_XGEN(b.x)], 1u);
;             asm volatile("s_waitcnt vmcnt(0)" ::: "memory");
;         } else {
;             XB_SPIN(xb_ld(&bar[XB_XGEN(b.x)]) == gen, bar);
.LBB0_569:
	s_or_b64 exec, exec, s[12:13]
	v_cvt_f32_u32_e32 v5, v3
	s_waitcnt vmcnt(0)
	v_readfirstlane_b32 s0, v4
	v_sub_u32_e32 v4, 0, v3
	v_rcp_iflag_f32_e32 v5, v5
	v_add_u32_e32 v6, s0, v1
	v_mul_f32_e32 v5, 0x4f7ffffe, v5
	v_cvt_u32_f32_e32 v5, v5
	v_mul_lo_u32 v1, v4, v5
	v_mul_hi_u32 v1, v5, v1
	v_add_u32_e32 v1, v5, v1
	v_mul_hi_u32 v1, v6, v1
	v_mul_lo_u32 v4, v1, v3
	v_sub_u32_e32 v4, v6, v4
	v_add_u32_e32 v5, 1, v1
	v_cmp_ge_u32_e32 vcc, v4, v3
	s_nop 1
	v_cndmask_b32_e32 v1, v1, v5, vcc
	v_sub_u32_e32 v5, v4, v3
	v_cndmask_b32_e32 v4, v4, v5, vcc
	v_add_u32_e32 v5, 1, v1
	v_cmp_ge_u32_e32 vcc, v4, v3
	v_add_u32_e32 v4, 1, v6
	s_nop 0
	v_cndmask_b32_e32 v1, v1, v5, vcc
	v_mul_lo_u32 v5, v3, v1
	v_add_u32_e32 v3, v5, v3
	v_cmp_ne_u32_e32 vcc, v4, v3
	s_and_saveexec_b64 s[0:1], vcc
	s_xor_b64 s[8:9], exec, s[0:1]
	s_cbranch_execz .LBB0_583
	s_waitcnt lgkmcnt(0)
	v_readlane_b32 s14, v254, 31
	v_readlane_b32 s15, v254, 32
	s_nop 4
	global_load_dword v2, v0, s[14:15] sc1
	s_waitcnt vmcnt(0)
	v_cmp_eq_u32_e32 vcc, v2, v1
	s_and_saveexec_b64 s[12:13], vcc
	s_cbranch_execz .LBB0_582
	s_mov_b32 s0, 1
	s_mov_b64 s[16:17], 0
	s_branch .LBB0_573

; __device__ __forceinline__ unsigned xb_ld(unsigned* p)              { return __hip_atomic_load(p, __ATOMIC_RELAXED, __HIP_MEMORY_SCOPE_AGENT); }
; __device__ __forceinline__ unsigned xb_add(unsigned* p, unsigned v) { return __hip_atomic_fetch_add(p, v, __ATOMIC_RELAXED, __HIP_MEMORY_SCOPE_AGENT); }
; #define XB_SPIN(cond, bar) do { unsigned _sp = 0; while (cond) { __builtin_amdgcn_s_sleep(1); \
;     if ((++_sp & 255u) == 0u) { if (xb_ld(&(bar)[XB_TMO])) break; if (_sp > XB_SPIN_CAP) { atomicAdd(&(bar)[XB_TMO], 1u); break; } } } } while (0)
; __device__ __forceinline__ void xcd_barrier(const XcdBarrier& b) {
;     ...
;         const unsigned old = xb_add(&bar[XB_XSUB(b.x)], 1u);
;         const unsigned gen = old / nloc;
;         if (old + 1u == (gen + 1u) * nloc) {
;             __builtin_amdgcn_fence(__ATOMIC_RELEASE, "agent");
;             asm volatile("s_waitcnt vmcnt(0)" ::: "memory");
;             const unsigned og = xb_add(&bar[XB_TOP], 1u);
;             const unsigned tg = og / nx;
;             if (og + 1u == (tg + 1u) * nx) xb_add(&bar[XB_TOPGEN], 1u);
;             else XB_SPIN(xb_ld(&bar[XB_TOPGEN]) == tg, bar);
;             __builtin_amdgcn_fence(__ATOMIC_ACQUIRE, "agent");
;             xb_add(&bar[XB_XGEN(b.x)], 1u);
;             asm volatile("s_waitcnt vmcnt(0)" ::: "memory");
;         } else {
;             XB_SPIN(xb_ld(&bar[XB_XGEN(b.x)]) == gen, bar);
.LBB0_630:
	s_or_b64 exec, exec, s[14:15]
	v_cvt_f32_u32_e32 v5, v3
	s_waitcnt vmcnt(0)
	v_readfirstlane_b32 s0, v4
	v_sub_u32_e32 v4, 0, v3
	v_rcp_iflag_f32_e32 v5, v5
	v_add_u32_e32 v6, s0, v1
	v_mul_f32_e32 v5, 0x4f7ffffe, v5
	v_cvt_u32_f32_e32 v5, v5
	v_mul_lo_u32 v1, v4, v5
	v_mul_hi_u32 v1, v5, v1
	v_add_u32_e32 v1, v5, v1
	v_mul_hi_u32 v1, v6, v1
	v_mul_lo_u32 v4, v1, v3
	v_sub_u32_e32 v4, v6, v4
	v_add_u32_e32 v5, 1, v1
	v_cmp_ge_u32_e32 vcc, v4, v3
	s_nop 1
	v_cndmask_b32_e32 v1, v1, v5, vcc
	v_sub_u32_e32 v5, v4, v3
	v_cndmask_b32_e32 v4, v4, v5, vcc
	v_add_u32_e32 v5, 1, v1
	v_cmp_ge_u32_e32 vcc, v4, v3
	v_add_u32_e32 v4, 1, v6
	s_nop 0
	v_cndmask_b32_e32 v1, v1, v5, vcc
	v_mul_lo_u32 v5, v3, v1
	v_add_u32_e32 v3, v5, v3
	v_cmp_ne_u32_e32 vcc, v4, v3
	s_and_saveexec_b64 s[0:1], vcc
	s_xor_b64 s[12:13], exec, s[0:1]
	s_cbranch_execz .LBB0_644
	s_waitcnt lgkmcnt(0)
	v_readlane_b32 s16, v254, 31
	v_readlane_b32 s17, v254, 32
	s_nop 4
	global_load_dword v2, v0, s[16:17] sc1
	s_waitcnt vmcnt(0)
	v_cmp_eq_u32_e32 vcc, v2, v1
	s_and_saveexec_b64 s[14:15], vcc
	s_cbranch_execz .LBB0_643
	s_mov_b32 s0, 1
	s_mov_b64 s[18:19], 0
	s_branch .LBB0_634

; __device__ __forceinline__ unsigned xb_ld(unsigned* p)              { return __hip_atomic_load(p, __ATOMIC_RELAXED, __HIP_MEMORY_SCOPE_AGENT); }
; __device__ __forceinline__ unsigned xb_add(unsigned* p, unsigned v) { return __hip_atomic_fetch_add(p, v, __ATOMIC_RELAXED, __HIP_MEMORY_SCOPE_AGENT); }
; #define XB_SPIN(cond, bar) do { unsigned _sp = 0; while (cond) { __builtin_amdgcn_s_sleep(1); \
;     if ((++_sp & 255u) == 0u) { if (xb_ld(&(bar)[XB_TMO])) break; if (_sp > XB_SPIN_CAP) { atomicAdd(&(bar)[XB_TMO], 1u); break; } } } } while (0)
; __device__ __forceinline__ void xcd_barrier(const XcdBarrier& b) {
;     ...
;         const unsigned old = xb_add(&bar[XB_XSUB(b.x)], 1u);
;         const unsigned gen = old / nloc;
;         if (old + 1u == (gen + 1u) * nloc) {
;             __builtin_amdgcn_fence(__ATOMIC_RELEASE, "agent");
;             asm volatile("s_waitcnt vmcnt(0)" ::: "memory");
;             const unsigned og = xb_add(&bar[XB_TOP], 1u);
;             const unsigned tg = og / nx;
;             if (og + 1u == (tg + 1u) * nx) xb_add(&bar[XB_TOPGEN], 1u);
;             else XB_SPIN(xb_ld(&bar[XB_TOPGEN]) == tg, bar);
;             __builtin_amdgcn_fence(__ATOMIC_ACQUIRE, "agent");
;             xb_add(&bar[XB_XGEN(b.x)], 1u);
;             asm volatile("s_waitcnt vmcnt(0)" ::: "memory");
;         } else {
;             XB_SPIN(xb_ld(&bar[XB_XGEN(b.x)]) == gen, bar);
.LBB0_1134:
	s_or_b64 exec, exec, s[10:11]
	v_cvt_f32_u32_e32 v5, v3
	s_waitcnt vmcnt(0)
	v_readfirstlane_b32 s0, v4
	v_sub_u32_e32 v4, 0, v3
	v_rcp_iflag_f32_e32 v5, v5
	v_add_u32_e32 v6, s0, v1
	v_mul_f32_e32 v5, 0x4f7ffffe, v5
	v_cvt_u32_f32_e32 v5, v5
	v_mul_lo_u32 v1, v4, v5
	v_mul_hi_u32 v1, v5, v1
	v_add_u32_e32 v1, v5, v1
	v_mul_hi_u32 v1, v6, v1
	v_mul_lo_u32 v4, v1, v3
	v_sub_u32_e32 v4, v6, v4
	v_add_u32_e32 v5, 1, v1
	v_cmp_ge_u32_e32 vcc, v4, v3
	s_nop 1
	v_cndmask_b32_e32 v1, v1, v5, vcc
	v_sub_u32_e32 v5, v4, v3
	v_cndmask_b32_e32 v4, v4, v5, vcc
	v_add_u32_e32 v5, 1, v1
	v_cmp_ge_u32_e32 vcc, v4, v3
	v_add_u32_e32 v4, 1, v6
	s_nop 0
	v_cndmask_b32_e32 v1, v1, v5, vcc
	v_mul_lo_u32 v5, v3, v1
	v_add_u32_e32 v3, v5, v3
	v_cmp_ne_u32_e32 vcc, v4, v3
	s_and_saveexec_b64 s[0:1], vcc
	s_xor_b64 s[8:9], exec, s[0:1]
	s_cbranch_execz .LBB0_1148
	s_waitcnt lgkmcnt(0)
	v_readlane_b32 s12, v254, 31
	v_readlane_b32 s13, v254, 32
	s_nop 4
	global_load_dword v2, v0, s[12:13] sc1
	s_waitcnt vmcnt(0)
	v_cmp_eq_u32_e32 vcc, v2, v1
	s_and_saveexec_b64 s[10:11], vcc
	s_cbranch_execz .LBB0_1147
	s_mov_b32 s0, 1
	s_mov_b64 s[14:15], 0
	s_branch .LBB0_1138

; __device__ __forceinline__ unsigned xb_ld(unsigned* p)              { return __hip_atomic_load(p, __ATOMIC_RELAXED, __HIP_MEMORY_SCOPE_AGENT); }
; __device__ __forceinline__ unsigned xb_add(unsigned* p, unsigned v) { return __hip_atomic_fetch_add(p, v, __ATOMIC_RELAXED, __HIP_MEMORY_SCOPE_AGENT); }
; #define XB_SPIN(cond, bar) do { unsigned _sp = 0; while (cond) { __builtin_amdgcn_s_sleep(1); \
;     if ((++_sp & 255u) == 0u) { if (xb_ld(&(bar)[XB_TMO])) break; if (_sp > XB_SPIN_CAP) { atomicAdd(&(bar)[XB_TMO], 1u); break; } } } } while (0)
; __device__ __forceinline__ void xcd_barrier(const XcdBarrier& b) {
;     ...
;         const unsigned old = xb_add(&bar[XB_XSUB(b.x)], 1u);
;         const unsigned gen = old / nloc;
;         if (old + 1u == (gen + 1u) * nloc) {
;             __builtin_amdgcn_fence(__ATOMIC_RELEASE, "agent");
;             asm volatile("s_waitcnt vmcnt(0)" ::: "memory");
;             const unsigned og = xb_add(&bar[XB_TOP], 1u);
;             const unsigned tg = og / nx;
;             if (og + 1u == (tg + 1u) * nx) xb_add(&bar[XB_TOPGEN], 1u);
;             else XB_SPIN(xb_ld(&bar[XB_TOPGEN]) == tg, bar);
;             __builtin_amdgcn_fence(__ATOMIC_ACQUIRE, "agent");
;             xb_add(&bar[XB_XGEN(b.x)], 1u);
;             asm volatile("s_waitcnt vmcnt(0)" ::: "memory");
;         } else {
;             XB_SPIN(xb_ld(&bar[XB_XGEN(b.x)]) == gen, bar);
.LBB0_2078:
	s_or_b64 exec, exec, s[8:9]
	v_cvt_f32_u32_e32 v5, v3
	s_waitcnt vmcnt(0)
	v_readfirstlane_b32 s3, v4
	v_sub_u32_e32 v4, 0, v3
	v_rcp_iflag_f32_e32 v5, v5
	v_add_u32_e32 v6, s3, v1
	v_mul_f32_e32 v5, 0x4f7ffffe, v5
	v_cvt_u32_f32_e32 v5, v5
	v_mul_lo_u32 v1, v4, v5
	v_mul_hi_u32 v1, v5, v1
	v_add_u32_e32 v1, v5, v1
	v_mul_hi_u32 v1, v6, v1
	v_mul_lo_u32 v4, v1, v3
	v_sub_u32_e32 v4, v6, v4
	v_add_u32_e32 v5, 1, v1
	v_cmp_ge_u32_e32 vcc, v4, v3
	s_nop 1
	v_cndmask_b32_e32 v1, v1, v5, vcc
	v_sub_u32_e32 v5, v4, v3
	v_cndmask_b32_e32 v4, v4, v5, vcc
	v_add_u32_e32 v5, 1, v1
	v_cmp_ge_u32_e32 vcc, v4, v3
	v_add_u32_e32 v4, 1, v6
	s_nop 0
	v_cndmask_b32_e32 v1, v1, v5, vcc
	v_mul_lo_u32 v5, v3, v1
	v_add_u32_e32 v3, v5, v3
	v_cmp_ne_u32_e32 vcc, v4, v3
	s_and_saveexec_b64 s[6:7], vcc
	s_xor_b64 s[6:7], exec, s[6:7]
	s_cbranch_execz .LBB0_2092
	s_waitcnt lgkmcnt(0)
	v_readlane_b32 s10, v254, 31
	v_readlane_b32 s11, v254, 32
	s_nop 4
	global_load_dword v2, v0, s[10:11] sc1
	s_waitcnt vmcnt(0)
	v_cmp_eq_u32_e32 vcc, v2, v1
	s_and_saveexec_b64 s[8:9], vcc
	s_cbranch_execz .LBB0_2091
	s_mov_b32 s3, 1
	s_mov_b64 s[12:13], 0
	s_branch .LBB0_2082

; __device__ __forceinline__ unsigned xb_ld(unsigned* p)              { return __hip_atomic_load(p, __ATOMIC_RELAXED, __HIP_MEMORY_SCOPE_AGENT); }
; __device__ __forceinline__ unsigned xb_add(unsigned* p, unsigned v) { return __hip_atomic_fetch_add(p, v, __ATOMIC_RELAXED, __HIP_MEMORY_SCOPE_AGENT); }
; #define XB_SPIN(cond, bar) do { unsigned _sp = 0; while (cond) { __builtin_amdgcn_s_sleep(1); \
;     if ((++_sp & 255u) == 0u) { if (xb_ld(&(bar)[XB_TMO])) break; if (_sp > XB_SPIN_CAP) { atomicAdd(&(bar)[XB_TMO], 1u); break; } } } } while (0)
; __device__ __forceinline__ void xcd_barrier(const XcdBarrier& b) {
;     ...
;         const unsigned old = xb_add(&bar[XB_XSUB(b.x)], 1u);
;         const unsigned gen = old / nloc;
;         if (old + 1u == (gen + 1u) * nloc) {
;             __builtin_amdgcn_fence(__ATOMIC_RELEASE, "agent");
;             asm volatile("s_waitcnt vmcnt(0)" ::: "memory");
;             const unsigned og = xb_add(&bar[XB_TOP], 1u);
;             const unsigned tg = og / nx;
;             if (og + 1u == (tg + 1u) * nx) xb_add(&bar[XB_TOPGEN], 1u);
;             else XB_SPIN(xb_ld(&bar[XB_TOPGEN]) == tg, bar);
;             __builtin_amdgcn_fence(__ATOMIC_ACQUIRE, "agent");
;             xb_add(&bar[XB_XGEN(b.x)], 1u);
;             asm volatile("s_waitcnt vmcnt(0)" ::: "memory");
;         } else {
;             XB_SPIN(xb_ld(&bar[XB_XGEN(b.x)]) == gen, bar);
.LBB0_2180:
	s_or_b64 exec, exec, s[10:11]
	v_cvt_f32_u32_e32 v5, v3
	s_waitcnt vmcnt(0)
	v_readfirstlane_b32 s3, v4
	v_sub_u32_e32 v4, 0, v3
	v_rcp_iflag_f32_e32 v5, v5
	v_add_u32_e32 v6, s3, v1
	v_mul_f32_e32 v5, 0x4f7ffffe, v5
	v_cvt_u32_f32_e32 v5, v5
	v_mul_lo_u32 v1, v4, v5
	v_mul_hi_u32 v1, v5, v1
	v_add_u32_e32 v1, v5, v1
	v_mul_hi_u32 v1, v6, v1
	v_mul_lo_u32 v4, v1, v3
	v_sub_u32_e32 v4, v6, v4
	v_add_u32_e32 v5, 1, v1
	v_cmp_ge_u32_e32 vcc, v4, v3
	s_nop 1
	v_cndmask_b32_e32 v1, v1, v5, vcc
	v_sub_u32_e32 v5, v4, v3
	v_cndmask_b32_e32 v4, v4, v5, vcc
	v_add_u32_e32 v5, 1, v1
	v_cmp_ge_u32_e32 vcc, v4, v3
	v_add_u32_e32 v4, 1, v6
	s_nop 0
	v_cndmask_b32_e32 v1, v1, v5, vcc
	v_mul_lo_u32 v5, v3, v1
	v_add_u32_e32 v3, v5, v3
	v_cmp_ne_u32_e32 vcc, v4, v3
	s_and_saveexec_b64 s[4:5], vcc
	s_xor_b64 s[8:9], exec, s[4:5]
	s_cbranch_execz .LBB0_2194
	s_waitcnt lgkmcnt(0)
	v_readlane_b32 s12, v254, 31
	v_readlane_b32 s13, v254, 32
	s_nop 4
	global_load_dword v2, v0, s[12:13] sc1
	s_waitcnt vmcnt(0)
	v_cmp_eq_u32_e32 vcc, v2, v1
	s_and_saveexec_b64 s[10:11], vcc
	s_cbranch_execz .LBB0_2193
	s_mov_b32 s3, 1
	s_mov_b64 s[14:15], 0
	s_branch .LBB0_2184
